# gdn_seq: next chunk's LDS-DMA fetches issued in one burst as soon as the staging regions are free (the real pass is memory-latency bound)
# baseline (speedup 1.0000x reference)
.LBB0_552:
	v_add_u32_e32 v1, 0x100, v1
	s_movk_i32 s8, 0xfff
	v_cmp_lt_u32_e32 vcc, s8, v1
	ds_write_b16 v0, v113
	s_or_b64 s[0:1], vcc, s[0:1]
	v_add_u32_e32 v0, 0x200, v0
	s_andn2_b64 exec, exec, s[0:1]
	s_cbranch_execnz .LBB0_552
	s_or_b64 exec, exec, s[0:1]
	s_ashr_i32 s22, s24, 4
	s_bfe_u32 s25, s24, 0x20002
	s_lshl_b32 s0, s22, 2
	s_or_b32 s0, s0, s25
	s_lshl_b32 s18, s0, 5
	s_ashr_i32 s19, s18, 31
	s_mul_i32 s1, s0, 0x240000
	s_mul_hi_i32 s8, s18, 0x12000
	s_add_u32 s16, s30, s1
	s_addc_u32 s17, s31, s8
	v_mov_b32_e32 v143, v113
	v_lshl_add_u64 v[0:1], v[116:117], 1, s[16:17]
	s_lshl_b32 s1, s24, 5
	v_lshl_add_u64 v[0:1], v[0:1], 0, v[142:143]
	s_and_b32 s8, s1, 0x60
	v_add_co_u32_e32 v6, vcc, s26, v0
	s_waitcnt vmcnt(18)
	v_or_b32_e32 v22, s8, v98
	s_mov_b64 s[46:47], 0x4000
	v_addc_co_u32_e32 v7, vcc, 0, v1, vcc
	v_add_u32_e32 v112, v22, v173
	v_readlane_b32 s68, v251, 8
	v_lshl_add_u64 v[2:3], v[0:1], 0, s[46:47]
	v_lshl_add_u64 v[4:5], v[0:1], 0, s[10:11]
	v_add_co_u32_e32 v0, vcc, s42, v0
	v_or_b32_e32 v8, v22, v173
	v_lshlrev_b64 v[80:81], 1, v[112:113]
	v_readlane_b32 s72, v251, 12
	v_readlane_b32 s73, v251, 13
	v_addc_co_u32_e32 v1, vcc, 0, v1, vcc
	v_lshlrev_b32_e32 v36, 1, v8
	v_lshl_add_u64 v[8:9], s[16:17], 0, v[80:81]
	v_add_u32_e32 v56, v22, v174
	v_mov_b32_e32 v57, v113
	v_add_u32_e32 v58, v22, v175
	v_mov_b32_e32 v59, v113
	v_add_u32_e32 v112, v22, v176
	v_readlane_b32 s74, v251, 14
	v_readlane_b32 s75, v251, 15
	v_readlane_b32 s76, v251, 16
	v_readlane_b32 s77, v251, 17
	v_readlane_b32 s78, v251, 18
	v_readlane_b32 s79, v251, 19
	s_mov_b64 s[48:49], s[72:73]
	global_load_dwordx4 v[32:35], v[6:7], off
	global_load_dwordx4 v[44:47], v[0:1], off
	global_load_dwordx4 v[12:15], v[2:3], off offset:64
	global_load_dwordx4 v[16:19], v[2:3], off offset:128
	global_load_dwordx4 v[28:31], v[4:5], off offset:64
	s_nop 0
	global_load_dwordx4 v[0:3], v[2:3], off offset:192
	s_nop 0
	global_load_dwordx4 v[24:27], v[4:5], off offset:128
	s_nop 0
	global_load_dwordx4 v[4:7], v[4:5], off offset:192
	v_lshl_add_u64 v[10:11], v[56:57], 1, s[16:17]
	v_lshl_add_u64 v[20:21], v[58:59], 1, s[16:17]
	v_lshl_add_u64 v[22:23], v[112:113], 1, s[16:17]
	global_load_ushort v186, v36, s[16:17]
	global_load_ushort v188, v[8:9], off offset:256
	global_load_ushort v185, v[8:9], off offset:512
	global_load_ushort v89, v[8:9], off offset:768
	global_load_ushort v187, v[10:11], off offset:32
	global_load_ushort v189, v[20:21], off offset:32
	global_load_ushort v190, v[22:23], off offset:32
	global_load_ushort v91, v[8:9], off offset:32
	s_lshl_b64 s[18:19], s[18:19], 2
	s_mov_b64 s[52:53], s[76:77]
	v_lshl_add_u64 v[8:9], v[118:119], 1, s[16:17]
	s_add_u32 s46, s52, s18
	v_lshl_add_u64 v[8:9], v[8:9], 0, v[142:143]
	s_addc_u32 s47, s53, s19
	v_lshl_add_u64 v[10:11], v[8:9], 0, s[14:15]
	v_lshl_add_u64 v[20:21], s[16:17], 0, v[142:143]
	v_add_co_u32_e32 v8, vcc, s43, v8
	global_load_dword v88, v113, s[46:47]
	s_nop 0
	v_addc_co_u32_e32 v9, vcc, 0, v9, vcc
	v_lshl_add_u64 v[20:21], v[120:121], 1, v[20:21]
	s_mov_b64 s[46:47], 0xc000
	s_mov_b32 s1, 0xc000
	v_lshl_add_u64 v[22:23], v[20:21], 0, s[46:47]
	v_add_co_u32_e32 v20, vcc, s1, v20
	s_ashr_i32 s23, s22, 31
	s_nop 0
	v_addc_co_u32_e32 v21, vcc, 0, v21, vcc
	global_load_dwordx4 v[52:55], v[8:9], off
	global_load_dwordx4 v[48:51], v[10:11], off offset:64
	s_nop 0
	global_load_dwordx4 v[8:11], v[22:23], off offset:2048
	global_load_dwordx4 v[36:39], v[22:23], off offset:64
	global_load_dwordx4 v[40:43], v[20:21], off
	s_nop 0
	global_load_dwordx4 v[20:23], v[22:23], off offset:2112
	s_add_u32 s18, s3, s18
	s_addc_u32 s19, s4, s19
	s_lshl_b64 s[22:23], s[22:23], 22
	s_lshl_b32 s25, s25, 9
	s_and_b32 s24, s24, 3
	s_or_b32 s22, s22, s25
	s_lshl_b32 s24, s24, 7
	v_lshlrev_b32_e32 v84, 1, v56
	s_or_b32 s22, s22, s24
	v_mov_b32_e32 v56, 0
	s_mov_b32 s1, 0
	v_lshlrev_b32_e32 v112, 1, v112
	v_lshlrev_b32_e32 v82, 1, v58
	v_mov_b32_e32 v83, v113
	v_mov_b32_e32 v85, v113
	v_lshl_add_u64 v[86:87], v[140:141], 0, s[22:23]
	v_mov_b32_e32 v57, v56
	v_mov_b32_e32 v58, v56
	v_mov_b32_e32 v59, v56
	v_mov_b32_e32 v64, v56
	v_mov_b32_e32 v65, v56
	v_mov_b32_e32 v66, v56
	v_mov_b32_e32 v67, v56
	v_mov_b32_e32 v68, v56
	v_mov_b32_e32 v69, v56
	v_mov_b32_e32 v70, v56
	v_mov_b32_e32 v71, v56
	v_mov_b32_e32 v60, v56
	v_mov_b32_e32 v61, v56
	v_mov_b32_e32 v62, v56
	v_mov_b32_e32 v63, v56
	v_readlane_b32 s69, v251, 9
	v_readlane_b32 s70, v251, 10
	v_readlane_b32 s71, v251, 11
	v_readlane_b32 s80, v251, 20
	v_readlane_b32 s81, v251, 21
	v_readlane_b32 s82, v251, 22
	v_readlane_b32 s83, v251, 23
	s_mov_b64 s[50:51], s[74:75]
	s_mov_b64 s[54:55], s[78:79]
	s_waitcnt lgkmcnt(0)
	s_barrier
	v_and_b32_e32 v242, 63, v162
	v_lshrrev_b32_e32 v243, 6, v162
	v_and_b32_e32 v244, 15, v242
	v_lshrrev_b32_e32 v245, 4, v242
	v_readfirstlane_b32 s56, v243
	v_xor_b32_e32 v250, v244, v245
	v_lshlrev_b32_e32 v253, 12, v243
	v_lshl_add_u32 v253, v245, 8, v253
	v_add_u32_e32 v253, 0x4000, v253
	v_xor_b32_e32 v254, 0, v250
	v_lshl_add_u32 v204, v254, 4, v253
	v_xor_b32_e32 v254, 4, v250
	v_lshl_add_u32 v205, v254, 4, v253
	v_add_u32_e32 v205, 0x400, v205
	v_xor_b32_e32 v254, 8, v250
	v_lshl_add_u32 v206, v254, 4, v253
	v_add_u32_e32 v206, 0x800, v206
	v_xor_b32_e32 v254, 12, v250
	v_lshl_add_u32 v207, v254, 4, v253
	v_add_u32_e32 v207, 0xc00, v207
	v_lshrrev_b32_e32 v253, 3, v242
	v_and_b32_e32 v254, 7, v242
	v_xor_b32_e32 v254, v254, v253
	v_lshlrev_b32_e32 v254, 4, v254
	v_lshl_add_u32 v254, v253, 7, v254
	v_lshl_add_u32 v210, v243, 12, v254
	v_add_u32_e32 v210, 0xc000, v210
	v_lshl_add_u32 v211, v243, 11, v254
	v_add_u32_e32 v211, 0x10000, v211
	v_lshl_add_u32 v253, v243, 2, v245
	v_lshlrev_b32_e32 v212, 10, v253
	v_add_u32_e32 v254, s8, v244
	v_lshl_add_u32 v212, v254, 1, v212
	v_lshlrev_b32_e32 v253, 12, v243
	v_lshl_add_u32 v253, v244, 8, v253
	v_add_u32_e32 v253, 0x3400, v253
	v_xor_b32_e32 v254, 0, v250
	v_lshl_add_u32 v213, v254, 4, v253
	v_xor_b32_e32 v254, 4, v250
	v_lshl_add_u32 v214, v254, 4, v253
	v_xor_b32_e32 v254, 8, v250
	v_lshl_add_u32 v215, v254, 4, v253
	v_xor_b32_e32 v254, 12, v250
	v_lshl_add_u32 v216, v254, 4, v253
	v_and_b32_e32 v254, 7, v244
	v_xor_b32_e32 v250, v254, v245
	v_lshlrev_b32_e32 v253, 7, v244
	v_lshl_add_u32 v242, v243, 12, v253
	v_add_u32_e32 v242, 0xb400, v242
	v_lshl_add_u32 v253, v243, 11, v253
	v_add_u32_e32 v253, 0x0, v253
	v_xor_b32_e32 v254, 0, v250
	v_lshl_add_u32 v217, v254, 4, v242
	v_lshl_add_u32 v221, v254, 4, v253
	v_xor_b32_e32 v254, 4, v250
	v_lshl_add_u32 v220, v254, 4, v242
	v_lshl_add_u32 v222, v254, 4, v253
	v_mul_u32_u24_e32 v253, 0x110, v244
	v_add_u32_e32 v253, 0x10c00, v253
	v_lshl_add_u32 v246, v245, 4, v253
	v_lshl_add_u32 v249, v245, 3, v253
	v_lshl_add_u32 v249, v243, 6, v249
	v_mul_u32_u24_e32 v253, 0x90, v244
	v_add_u32_e32 v253, 0x2200, v253
	v_lshl_add_u32 v248, v245, 4, v253
	v_lshl_add_u32 v247, v245, 3, v253
	v_lshl_add_u32 v247, v243, 5, v247
	s_add_u32 s20, s16, 0x12000
	s_addc_u32 s21, s17, 0
	s_add_u32 s22, s20, 0x4000
	s_addc_u32 s23, s21, 0
	s_mov_b64 s[46:47], s[18:19]
	s_mov_b64 s[50:51], 0x20000
	s_lshl_b32 s52, s56, 12
	s_add_u32 s53, s52, 0x7400
	s_add_u32 s54, s52, 0xb400
	s_add_u32 s52, s52, 0x3400
	s_lshl_b32 s55, s56, 11
	s_add_u32 s55, s55, 0x0
	s_waitcnt vmcnt(15)
	ds_read_b128 v[148:151], v246 offset:0
	ds_read_b128 v[192:195], v246 offset:4352
	ds_read_b128 v[196:199], v246 offset:64
	ds_read_b128 v[200:203], v246 offset:4416
	s_add_u32 m0, s52, 0x0
	s_nop 0
	global_load_lds_dwordx4 v204, s[20:21]
	s_add_u32 m0, s52, 0x400
	s_nop 0
	global_load_lds_dwordx4 v205, s[20:21]
	s_add_u32 m0, s52, 0x800
	s_nop 0
	global_load_lds_dwordx4 v206, s[20:21]
	s_add_u32 m0, s52, 0xc00
	s_nop 0
	global_load_lds_dwordx4 v207, s[20:21]
	s_add_u32 m0, s53, 0x0
	s_nop 0
	global_load_lds_dwordx4 v204, s[22:23]
	s_add_u32 m0, s53, 0x400
	s_nop 0
	global_load_lds_dwordx4 v205, s[22:23]
	s_add_u32 m0, s53, 0x800
	s_nop 0
	global_load_lds_dwordx4 v206, s[22:23]
	s_add_u32 m0, s53, 0xc00
	s_nop 0
	global_load_lds_dwordx4 v207, s[22:23]
	s_waitcnt lgkmcnt(3)
	v_mfma_f32_16x16x32_bf16 v[92:95], v[32:35], v[148:151], 0
	v_mfma_f32_16x16x32_bf16 v[72:75], v[148:151], v[44:47], 0
	s_waitcnt lgkmcnt(2)
	v_mfma_f32_16x16x32_bf16 v[144:147], v[32:35], v[192:195], 0
	v_mfma_f32_16x16x32_bf16 v[76:79], v[192:195], v[44:47], 0
	ds_read_b128 v[148:151], v246 offset:128
	ds_read_b128 v[192:195], v246 offset:4480
	s_waitcnt lgkmcnt(3)
	v_mfma_f32_16x16x32_bf16 v[92:95], v[12:15], v[196:199], v[92:95]
	v_mfma_f32_16x16x32_bf16 v[72:75], v[196:199], v[28:31], v[72:75]
	s_waitcnt lgkmcnt(2)
	v_mfma_f32_16x16x32_bf16 v[144:147], v[12:15], v[200:203], v[144:147]
	v_mfma_f32_16x16x32_bf16 v[76:79], v[200:203], v[28:31], v[76:79]
	ds_read_b128 v[196:199], v246 offset:192
	ds_read_b128 v[200:203], v246 offset:4544
	s_waitcnt lgkmcnt(3)
	v_mfma_f32_16x16x32_bf16 v[92:95], v[16:19], v[148:151], v[92:95]
	v_mfma_f32_16x16x32_bf16 v[72:75], v[148:151], v[24:27], v[72:75]
	s_waitcnt lgkmcnt(2)
	v_mfma_f32_16x16x32_bf16 v[144:147], v[16:19], v[192:195], v[144:147]
	v_mfma_f32_16x16x32_bf16 v[76:79], v[192:195], v[24:27], v[76:79]
	s_waitcnt lgkmcnt(1)
	v_mfma_f32_16x16x32_bf16 v[92:95], v[0:3], v[196:199], v[92:95]
	v_mfma_f32_16x16x32_bf16 v[72:75], v[196:199], v[4:7], v[72:75]
	s_waitcnt lgkmcnt(0)
	v_mfma_f32_16x16x32_bf16 v[144:147], v[0:3], v[200:203], v[144:147]
	v_mfma_f32_16x16x32_bf16 v[76:79], v[200:203], v[4:7], v[76:79]
	s_waitcnt vmcnt(14)
	v_mov_b32_e32 v255, v88
	s_nop 7
	v_lshlrev_b32_e32 v242, 16, v186
	v_lshlrev_b32_e32 v243, 16, v188
	v_lshlrev_b32_e32 v244, 16, v185
	v_lshlrev_b32_e32 v245, 16, v89
	v_sub_f32_e32 v242, v242, v92
	v_sub_f32_e32 v243, v243, v93
	v_sub_f32_e32 v244, v244, v94
	v_sub_f32_e32 v245, v245, v95
	v_cvt_pk_bf16_f32 v242, v242, v243
	v_cvt_pk_bf16_f32 v243, v244, v245
	ds_write_b64 v247, v[242:243]
	v_lshlrev_b32_e32 v242, 16, v91
	v_lshlrev_b32_e32 v243, 16, v187
	v_lshlrev_b32_e32 v244, 16, v189
	v_lshlrev_b32_e32 v245, 16, v190
	v_sub_f32_e32 v242, v242, v144
	v_sub_f32_e32 v243, v243, v145
	v_sub_f32_e32 v244, v244, v146
	v_sub_f32_e32 v245, v245, v147
	v_cvt_pk_bf16_f32 v242, v242, v243
	v_cvt_pk_bf16_f32 v243, v244, v245
	ds_write_b64 v247, v[242:243] offset:2304
	global_load_ushort v186, v212, s[20:21] offset:0
	global_load_ushort v188, v212, s[20:21] offset:256
	global_load_ushort v185, v212, s[20:21] offset:512
	global_load_ushort v89, v212, s[20:21] offset:768
	global_load_ushort v91, v212, s[20:21] offset:32
	global_load_ushort v187, v212, s[20:21] offset:288
	global_load_ushort v189, v212, s[20:21] offset:544
	global_load_ushort v190, v212, s[20:21] offset:800
	global_load_dword v88, v113, s[46:47]
	s_waitcnt lgkmcnt(0)
	s_barrier
	s_waitcnt vmcnt(17)
	ds_read_b128 v[148:151], v248 offset:0
	ds_read_b128 v[192:195], v248 offset:2304
	ds_read_b128 v[196:199], v248 offset:64
	ds_read_b128 v[200:203], v248 offset:2368
	v_mul_f32_e32 v56, v56, v255
	v_mul_f32_e32 v57, v57, v255
	v_mul_f32_e32 v58, v58, v255
	v_mul_f32_e32 v59, v59, v255
	v_mul_f32_e32 v64, v64, v255
	v_mul_f32_e32 v65, v65, v255
	v_mul_f32_e32 v66, v66, v255
	v_mul_f32_e32 v67, v67, v255
	v_mul_f32_e32 v68, v68, v255
	v_mul_f32_e32 v69, v69, v255
	v_mul_f32_e32 v70, v70, v255
	v_mul_f32_e32 v71, v71, v255
	v_mul_f32_e32 v60, v60, v255
	v_mul_f32_e32 v61, v61, v255
	v_mul_f32_e32 v62, v62, v255
	v_mul_f32_e32 v63, v63, v255
	s_mov_b32 m0, s54
	s_nop 0
	global_load_lds_dwordx4 v210, s[20:21]
	s_nop 0
	global_load_lds_dwordx4 v210, s[20:21] offset:1024
	s_nop 0
	global_load_lds_dwordx4 v210, s[20:21] offset:2048
	s_nop 0
	global_load_lds_dwordx4 v210, s[20:21] offset:3072
	s_mov_b32 m0, s55
	s_nop 0
	global_load_lds_dwordx4 v211, s[20:21]
	s_nop 0
	global_load_lds_dwordx4 v211, s[20:21] offset:1024
	s_waitcnt lgkmcnt(3)
	v_mfma_f32_16x16x32_bf16 v[72:75], v[148:151], v[52:55], v[72:75]
	s_waitcnt lgkmcnt(2)
	v_mfma_f32_16x16x32_bf16 v[76:79], v[192:195], v[52:55], v[76:79]
	s_waitcnt lgkmcnt(1)
	v_mfma_f32_16x16x32_bf16 v[72:75], v[196:199], v[48:51], v[72:75]
	s_waitcnt lgkmcnt(0)
	v_mfma_f32_16x16x32_bf16 v[76:79], v[200:203], v[48:51], v[76:79]
	v_mfma_f32_16x16x32_bf16 v[56:59], v[40:43], v[148:151], v[56:59]
	v_mfma_f32_16x16x32_bf16 v[64:67], v[40:43], v[192:195], v[64:67]
	v_mfma_f32_16x16x32_bf16 v[56:59], v[36:39], v[196:199], v[56:59]
	v_mfma_f32_16x16x32_bf16 v[64:67], v[36:39], v[200:203], v[64:67]
	v_mfma_f32_16x16x32_bf16 v[68:71], v[8:11], v[148:151], v[68:71]
	v_mfma_f32_16x16x32_bf16 v[60:63], v[8:11], v[192:195], v[60:63]
	v_mfma_f32_16x16x32_bf16 v[68:71], v[20:23], v[196:199], v[68:71]
	v_mfma_f32_16x16x32_bf16 v[60:63], v[20:23], v[200:203], v[60:63]
	s_nop 3
	global_store_dwordx4 v[86:87], v[72:75], off
	global_store_dwordx4 v[86:87], v[76:79], off offset:64
	s_nop 7
	v_cvt_pk_bf16_f32 v242, v56, v57
	v_cvt_pk_bf16_f32 v243, v58, v59
	ds_write_b64 v249, v[242:243]
	v_cvt_pk_bf16_f32 v242, v64, v65
	v_cvt_pk_bf16_f32 v243, v66, v67
	ds_write_b64 v249, v[242:243] offset:4352
	v_cvt_pk_bf16_f32 v242, v68, v69
	v_cvt_pk_bf16_f32 v243, v70, v71
	ds_write_b64 v249, v[242:243] offset:32
	v_cvt_pk_bf16_f32 v242, v60, v61
	v_cvt_pk_bf16_f32 v243, v62, v63
	ds_write_b64 v249, v[242:243] offset:4384
	v_lshl_add_u64 v[86:87], v[86:87], 0, s[50:51]
	s_add_u32 s20, s20, 0x12000
	s_addc_u32 s21, s21, 0
	s_add_u32 s22, s22, 0x12000
	s_addc_u32 s23, s23, 0
	s_add_u32 s46, s46, 4
	s_addc_u32 s47, s47, 0
	s_waitcnt lgkmcnt(0)
	s_barrier
	s_waitcnt vmcnt(17)
	ds_read_b128 v[32:35], v213
	ds_read_b128 v[44:47], v213 offset:16384
	ds_read_b128 v[12:15], v214
	ds_read_b128 v[28:31], v214 offset:16384
	ds_read_b128 v[16:19], v215
	ds_read_b128 v[24:27], v215 offset:16384
	ds_read_b128 v[0:3], v216
	ds_read_b128 v[4:7], v216 offset:16384
	ds_read_b128 v[148:151], v246 offset:0
	ds_read_b128 v[192:195], v246 offset:4352
	ds_read_b128 v[196:199], v246 offset:64
	ds_read_b128 v[200:203], v246 offset:4416
	s_waitcnt lgkmcnt(4)
	s_add_u32 m0, s52, 0x0
	s_nop 0
	global_load_lds_dwordx4 v204, s[20:21]
	s_add_u32 m0, s52, 0x400
	s_nop 0
	global_load_lds_dwordx4 v205, s[20:21]
	s_add_u32 m0, s52, 0x800
	s_nop 0
	global_load_lds_dwordx4 v206, s[20:21]
	s_add_u32 m0, s52, 0xc00
	s_nop 0
	global_load_lds_dwordx4 v207, s[20:21]
	s_add_u32 m0, s53, 0x0
	s_nop 0
	global_load_lds_dwordx4 v204, s[22:23]
	s_add_u32 m0, s53, 0x400
	s_nop 0
	global_load_lds_dwordx4 v205, s[22:23]
	s_add_u32 m0, s53, 0x800
	s_nop 0
	global_load_lds_dwordx4 v206, s[22:23]
	s_add_u32 m0, s53, 0xc00
	s_nop 0
	global_load_lds_dwordx4 v207, s[22:23]
	s_waitcnt lgkmcnt(3)
	v_mfma_f32_16x16x32_bf16 v[92:95], v[32:35], v[148:151], 0
	v_mfma_f32_16x16x32_bf16 v[72:75], v[148:151], v[44:47], 0
	s_waitcnt lgkmcnt(2)
	v_mfma_f32_16x16x32_bf16 v[144:147], v[32:35], v[192:195], 0
	v_mfma_f32_16x16x32_bf16 v[76:79], v[192:195], v[44:47], 0
	ds_read_b128 v[148:151], v246 offset:128
	ds_read_b128 v[192:195], v246 offset:4480
	s_waitcnt lgkmcnt(3)
	v_mfma_f32_16x16x32_bf16 v[92:95], v[12:15], v[196:199], v[92:95]
	v_mfma_f32_16x16x32_bf16 v[72:75], v[196:199], v[28:31], v[72:75]
	s_waitcnt lgkmcnt(2)
	v_mfma_f32_16x16x32_bf16 v[144:147], v[12:15], v[200:203], v[144:147]
	v_mfma_f32_16x16x32_bf16 v[76:79], v[200:203], v[28:31], v[76:79]
	ds_read_b128 v[196:199], v246 offset:192
	ds_read_b128 v[200:203], v246 offset:4544
	s_waitcnt lgkmcnt(3)
	v_mfma_f32_16x16x32_bf16 v[92:95], v[16:19], v[148:151], v[92:95]
	v_mfma_f32_16x16x32_bf16 v[72:75], v[148:151], v[24:27], v[72:75]
	s_waitcnt lgkmcnt(2)
	v_mfma_f32_16x16x32_bf16 v[144:147], v[16:19], v[192:195], v[144:147]
	v_mfma_f32_16x16x32_bf16 v[76:79], v[192:195], v[24:27], v[76:79]
	s_waitcnt lgkmcnt(1)
	v_mfma_f32_16x16x32_bf16 v[92:95], v[0:3], v[196:199], v[92:95]
	v_mfma_f32_16x16x32_bf16 v[72:75], v[196:199], v[4:7], v[72:75]
	s_waitcnt lgkmcnt(0)
	v_mfma_f32_16x16x32_bf16 v[144:147], v[0:3], v[200:203], v[144:147]
	v_mfma_f32_16x16x32_bf16 v[76:79], v[200:203], v[4:7], v[76:79]
	s_waitcnt vmcnt(16)
	v_mov_b32_e32 v255, v88
	s_nop 7
	v_lshlrev_b32_e32 v242, 16, v186
	v_lshlrev_b32_e32 v243, 16, v188
	v_lshlrev_b32_e32 v244, 16, v185
	v_lshlrev_b32_e32 v245, 16, v89
	v_sub_f32_e32 v242, v242, v92
	v_sub_f32_e32 v243, v243, v93
	v_sub_f32_e32 v244, v244, v94
	v_sub_f32_e32 v245, v245, v95
	v_cvt_pk_bf16_f32 v242, v242, v243
	v_cvt_pk_bf16_f32 v243, v244, v245
	ds_write_b64 v247, v[242:243]
	v_lshlrev_b32_e32 v242, 16, v91
	v_lshlrev_b32_e32 v243, 16, v187
	v_lshlrev_b32_e32 v244, 16, v189
	v_lshlrev_b32_e32 v245, 16, v190
	v_sub_f32_e32 v242, v242, v144
	v_sub_f32_e32 v243, v243, v145
	v_sub_f32_e32 v244, v244, v146
	v_sub_f32_e32 v245, v245, v147
	v_cvt_pk_bf16_f32 v242, v242, v243
	v_cvt_pk_bf16_f32 v243, v244, v245
	ds_write_b64 v247, v[242:243] offset:2304
	global_load_ushort v186, v212, s[20:21] offset:0
	global_load_ushort v188, v212, s[20:21] offset:256
	global_load_ushort v185, v212, s[20:21] offset:512
	global_load_ushort v89, v212, s[20:21] offset:768
	global_load_ushort v91, v212, s[20:21] offset:32
	global_load_ushort v187, v212, s[20:21] offset:288
	global_load_ushort v189, v212, s[20:21] offset:544
	global_load_ushort v190, v212, s[20:21] offset:800
	global_load_dword v88, v113, s[46:47]
	s_waitcnt lgkmcnt(0)
	s_barrier
	s_waitcnt vmcnt(19)
	ds_read_b128 v[52:55], v221
	ds_read_b128 v[48:51], v222
	ds_read_b128 v[40:43], v217
	ds_read_b128 v[36:39], v220
	ds_read_b128 v[8:11], v217 offset:2048
	ds_read_b128 v[20:23], v220 offset:2048
	ds_read_b128 v[148:151], v248 offset:0
	ds_read_b128 v[192:195], v248 offset:2304
	ds_read_b128 v[196:199], v248 offset:64
	ds_read_b128 v[200:203], v248 offset:2368
	v_mul_f32_e32 v56, v56, v255
	v_mul_f32_e32 v57, v57, v255
	v_mul_f32_e32 v58, v58, v255
	v_mul_f32_e32 v59, v59, v255
	v_mul_f32_e32 v64, v64, v255
	v_mul_f32_e32 v65, v65, v255
	v_mul_f32_e32 v66, v66, v255
	v_mul_f32_e32 v67, v67, v255
	v_mul_f32_e32 v68, v68, v255
	v_mul_f32_e32 v69, v69, v255
	v_mul_f32_e32 v70, v70, v255
	v_mul_f32_e32 v71, v71, v255
	v_mul_f32_e32 v60, v60, v255
	v_mul_f32_e32 v61, v61, v255
	v_mul_f32_e32 v62, v62, v255
	v_mul_f32_e32 v63, v63, v255
	s_waitcnt lgkmcnt(4)
	s_mov_b32 m0, s54
	s_nop 0
	global_load_lds_dwordx4 v210, s[20:21]
	s_nop 0
	global_load_lds_dwordx4 v210, s[20:21] offset:1024
	s_nop 0
	global_load_lds_dwordx4 v210, s[20:21] offset:2048
	s_nop 0
	global_load_lds_dwordx4 v210, s[20:21] offset:3072
	s_mov_b32 m0, s55
	s_nop 0
	global_load_lds_dwordx4 v211, s[20:21]
	s_nop 0
	global_load_lds_dwordx4 v211, s[20:21] offset:1024
	s_waitcnt lgkmcnt(3)
	v_mfma_f32_16x16x32_bf16 v[72:75], v[148:151], v[52:55], v[72:75]
	s_waitcnt lgkmcnt(2)
	v_mfma_f32_16x16x32_bf16 v[76:79], v[192:195], v[52:55], v[76:79]
	s_waitcnt lgkmcnt(1)
	v_mfma_f32_16x16x32_bf16 v[72:75], v[196:199], v[48:51], v[72:75]
	s_waitcnt lgkmcnt(0)
	v_mfma_f32_16x16x32_bf16 v[76:79], v[200:203], v[48:51], v[76:79]
	v_mfma_f32_16x16x32_bf16 v[56:59], v[40:43], v[148:151], v[56:59]
	v_mfma_f32_16x16x32_bf16 v[64:67], v[40:43], v[192:195], v[64:67]
	v_mfma_f32_16x16x32_bf16 v[56:59], v[36:39], v[196:199], v[56:59]
	v_mfma_f32_16x16x32_bf16 v[64:67], v[36:39], v[200:203], v[64:67]
	v_mfma_f32_16x16x32_bf16 v[68:71], v[8:11], v[148:151], v[68:71]
	v_mfma_f32_16x16x32_bf16 v[60:63], v[8:11], v[192:195], v[60:63]
	v_mfma_f32_16x16x32_bf16 v[68:71], v[20:23], v[196:199], v[68:71]
	v_mfma_f32_16x16x32_bf16 v[60:63], v[20:23], v[200:203], v[60:63]
	s_nop 3
	global_store_dwordx4 v[86:87], v[72:75], off
	global_store_dwordx4 v[86:87], v[76:79], off offset:64
	s_nop 7
	v_cvt_pk_bf16_f32 v242, v56, v57
	v_cvt_pk_bf16_f32 v243, v58, v59
	ds_write_b64 v249, v[242:243]
	v_cvt_pk_bf16_f32 v242, v64, v65
	v_cvt_pk_bf16_f32 v243, v66, v67
	ds_write_b64 v249, v[242:243] offset:4352
	v_cvt_pk_bf16_f32 v242, v68, v69
	v_cvt_pk_bf16_f32 v243, v70, v71
	ds_write_b64 v249, v[242:243] offset:32
	v_cvt_pk_bf16_f32 v242, v60, v61
	v_cvt_pk_bf16_f32 v243, v62, v63
	ds_write_b64 v249, v[242:243] offset:4384
	v_lshl_add_u64 v[86:87], v[86:87], 0, s[50:51]
	s_add_u32 s20, s20, 0x12000
	s_addc_u32 s21, s21, 0
	s_add_u32 s22, s22, 0x12000
	s_addc_u32 s23, s23, 0
	s_add_u32 s46, s46, 4
	s_addc_u32 s47, s47, 0
	s_waitcnt lgkmcnt(0)
	s_barrier
	s_mov_b32 s1, 29
.Lseq_loop:
	s_waitcnt vmcnt(17)
	ds_read_b128 v[32:35], v213
	ds_read_b128 v[44:47], v213 offset:16384
	ds_read_b128 v[12:15], v214
	ds_read_b128 v[28:31], v214 offset:16384
	ds_read_b128 v[16:19], v215
	ds_read_b128 v[24:27], v215 offset:16384
	ds_read_b128 v[0:3], v216
	ds_read_b128 v[4:7], v216 offset:16384
	ds_read_b128 v[148:151], v246 offset:0
	ds_read_b128 v[192:195], v246 offset:4352
	ds_read_b128 v[196:199], v246 offset:64
	ds_read_b128 v[200:203], v246 offset:4416
	s_waitcnt lgkmcnt(4)
	s_add_u32 m0, s52, 0x0
	s_nop 0
	global_load_lds_dwordx4 v204, s[20:21]
	s_add_u32 m0, s52, 0x400
	s_nop 0
	global_load_lds_dwordx4 v205, s[20:21]
	s_add_u32 m0, s52, 0x800
	s_nop 0
	global_load_lds_dwordx4 v206, s[20:21]
	s_add_u32 m0, s52, 0xc00
	s_nop 0
	global_load_lds_dwordx4 v207, s[20:21]
	s_add_u32 m0, s53, 0x0
	s_nop 0
	global_load_lds_dwordx4 v204, s[22:23]
	s_add_u32 m0, s53, 0x400
	s_nop 0
	global_load_lds_dwordx4 v205, s[22:23]
	s_add_u32 m0, s53, 0x800
	s_nop 0
	global_load_lds_dwordx4 v206, s[22:23]
	s_add_u32 m0, s53, 0xc00
	s_nop 0
	global_load_lds_dwordx4 v207, s[22:23]
	s_waitcnt lgkmcnt(3)
	v_mfma_f32_16x16x32_bf16 v[92:95], v[32:35], v[148:151], 0
	v_mfma_f32_16x16x32_bf16 v[72:75], v[148:151], v[44:47], 0
	s_waitcnt lgkmcnt(2)
	v_mfma_f32_16x16x32_bf16 v[144:147], v[32:35], v[192:195], 0
	v_mfma_f32_16x16x32_bf16 v[76:79], v[192:195], v[44:47], 0
	ds_read_b128 v[148:151], v246 offset:128
	ds_read_b128 v[192:195], v246 offset:4480
	s_waitcnt lgkmcnt(3)
	v_mfma_f32_16x16x32_bf16 v[92:95], v[12:15], v[196:199], v[92:95]
	v_mfma_f32_16x16x32_bf16 v[72:75], v[196:199], v[28:31], v[72:75]
	s_waitcnt lgkmcnt(2)
	v_mfma_f32_16x16x32_bf16 v[144:147], v[12:15], v[200:203], v[144:147]
	v_mfma_f32_16x16x32_bf16 v[76:79], v[200:203], v[28:31], v[76:79]
	ds_read_b128 v[196:199], v246 offset:192
	ds_read_b128 v[200:203], v246 offset:4544
	s_waitcnt lgkmcnt(3)
	v_mfma_f32_16x16x32_bf16 v[92:95], v[16:19], v[148:151], v[92:95]
	v_mfma_f32_16x16x32_bf16 v[72:75], v[148:151], v[24:27], v[72:75]
	s_waitcnt lgkmcnt(2)
	v_mfma_f32_16x16x32_bf16 v[144:147], v[16:19], v[192:195], v[144:147]
	v_mfma_f32_16x16x32_bf16 v[76:79], v[192:195], v[24:27], v[76:79]
	s_waitcnt lgkmcnt(1)
	v_mfma_f32_16x16x32_bf16 v[92:95], v[0:3], v[196:199], v[92:95]
	v_mfma_f32_16x16x32_bf16 v[72:75], v[196:199], v[4:7], v[72:75]
	s_waitcnt lgkmcnt(0)
	v_mfma_f32_16x16x32_bf16 v[144:147], v[0:3], v[200:203], v[144:147]
	v_mfma_f32_16x16x32_bf16 v[76:79], v[200:203], v[4:7], v[76:79]
	s_waitcnt vmcnt(16)
	v_mov_b32_e32 v255, v88
	s_nop 7
	v_lshlrev_b32_e32 v242, 16, v186
	v_lshlrev_b32_e32 v243, 16, v188
	v_lshlrev_b32_e32 v244, 16, v185
	v_lshlrev_b32_e32 v245, 16, v89
	v_sub_f32_e32 v242, v242, v92
	v_sub_f32_e32 v243, v243, v93
	v_sub_f32_e32 v244, v244, v94
	v_sub_f32_e32 v245, v245, v95
	v_cvt_pk_bf16_f32 v242, v242, v243
	v_cvt_pk_bf16_f32 v243, v244, v245
	ds_write_b64 v247, v[242:243]
	v_lshlrev_b32_e32 v242, 16, v91
	v_lshlrev_b32_e32 v243, 16, v187
	v_lshlrev_b32_e32 v244, 16, v189
	v_lshlrev_b32_e32 v245, 16, v190
	v_sub_f32_e32 v242, v242, v144
	v_sub_f32_e32 v243, v243, v145
	v_sub_f32_e32 v244, v244, v146
	v_sub_f32_e32 v245, v245, v147
	v_cvt_pk_bf16_f32 v242, v242, v243
	v_cvt_pk_bf16_f32 v243, v244, v245
	ds_write_b64 v247, v[242:243] offset:2304
	global_load_ushort v186, v212, s[20:21] offset:0
	global_load_ushort v188, v212, s[20:21] offset:256
	global_load_ushort v185, v212, s[20:21] offset:512
	global_load_ushort v89, v212, s[20:21] offset:768
	global_load_ushort v91, v212, s[20:21] offset:32
	global_load_ushort v187, v212, s[20:21] offset:288
	global_load_ushort v189, v212, s[20:21] offset:544
	global_load_ushort v190, v212, s[20:21] offset:800
	global_load_dword v88, v113, s[46:47]
	s_waitcnt lgkmcnt(0)
	s_barrier
	s_waitcnt vmcnt(19)
	ds_read_b128 v[52:55], v221
	ds_read_b128 v[48:51], v222
	ds_read_b128 v[40:43], v217
	ds_read_b128 v[36:39], v220
	ds_read_b128 v[8:11], v217 offset:2048
	ds_read_b128 v[20:23], v220 offset:2048
	ds_read_b128 v[148:151], v248 offset:0
	ds_read_b128 v[192:195], v248 offset:2304
	ds_read_b128 v[196:199], v248 offset:64
	ds_read_b128 v[200:203], v248 offset:2368
	v_mul_f32_e32 v56, v56, v255
	v_mul_f32_e32 v57, v57, v255
	v_mul_f32_e32 v58, v58, v255
	v_mul_f32_e32 v59, v59, v255
	v_mul_f32_e32 v64, v64, v255
	v_mul_f32_e32 v65, v65, v255
	v_mul_f32_e32 v66, v66, v255
	v_mul_f32_e32 v67, v67, v255
	v_mul_f32_e32 v68, v68, v255
	v_mul_f32_e32 v69, v69, v255
	v_mul_f32_e32 v70, v70, v255
	v_mul_f32_e32 v71, v71, v255
	v_mul_f32_e32 v60, v60, v255
	v_mul_f32_e32 v61, v61, v255
	v_mul_f32_e32 v62, v62, v255
	v_mul_f32_e32 v63, v63, v255
	s_waitcnt lgkmcnt(4)
	s_mov_b32 m0, s54
	s_nop 0
	global_load_lds_dwordx4 v210, s[20:21]
	s_nop 0
	global_load_lds_dwordx4 v210, s[20:21] offset:1024
	s_nop 0
	global_load_lds_dwordx4 v210, s[20:21] offset:2048
	s_nop 0
	global_load_lds_dwordx4 v210, s[20:21] offset:3072
	s_mov_b32 m0, s55
	s_nop 0
	global_load_lds_dwordx4 v211, s[20:21]
	s_nop 0
	global_load_lds_dwordx4 v211, s[20:21] offset:1024
	s_waitcnt lgkmcnt(3)
	v_mfma_f32_16x16x32_bf16 v[72:75], v[148:151], v[52:55], v[72:75]
	s_waitcnt lgkmcnt(2)
	v_mfma_f32_16x16x32_bf16 v[76:79], v[192:195], v[52:55], v[76:79]
	s_waitcnt lgkmcnt(1)
	v_mfma_f32_16x16x32_bf16 v[72:75], v[196:199], v[48:51], v[72:75]
	s_waitcnt lgkmcnt(0)
	v_mfma_f32_16x16x32_bf16 v[76:79], v[200:203], v[48:51], v[76:79]
	v_mfma_f32_16x16x32_bf16 v[56:59], v[40:43], v[148:151], v[56:59]
	v_mfma_f32_16x16x32_bf16 v[64:67], v[40:43], v[192:195], v[64:67]
	v_mfma_f32_16x16x32_bf16 v[56:59], v[36:39], v[196:199], v[56:59]
	v_mfma_f32_16x16x32_bf16 v[64:67], v[36:39], v[200:203], v[64:67]
	v_mfma_f32_16x16x32_bf16 v[68:71], v[8:11], v[148:151], v[68:71]
	v_mfma_f32_16x16x32_bf16 v[60:63], v[8:11], v[192:195], v[60:63]
	v_mfma_f32_16x16x32_bf16 v[68:71], v[20:23], v[196:199], v[68:71]
	v_mfma_f32_16x16x32_bf16 v[60:63], v[20:23], v[200:203], v[60:63]
	s_nop 3
	global_store_dwordx4 v[86:87], v[72:75], off
	global_store_dwordx4 v[86:87], v[76:79], off offset:64
	s_nop 7
	v_cvt_pk_bf16_f32 v242, v56, v57
	v_cvt_pk_bf16_f32 v243, v58, v59
	ds_write_b64 v249, v[242:243]
	v_cvt_pk_bf16_f32 v242, v64, v65
	v_cvt_pk_bf16_f32 v243, v66, v67
	ds_write_b64 v249, v[242:243] offset:4352
	v_cvt_pk_bf16_f32 v242, v68, v69
	v_cvt_pk_bf16_f32 v243, v70, v71
	ds_write_b64 v249, v[242:243] offset:32
	v_cvt_pk_bf16_f32 v242, v60, v61
	v_cvt_pk_bf16_f32 v243, v62, v63
	ds_write_b64 v249, v[242:243] offset:4384
	v_lshl_add_u64 v[86:87], v[86:87], 0, s[50:51]
	s_add_u32 s20, s20, 0x12000
	s_addc_u32 s21, s21, 0
	s_add_u32 s22, s22, 0x12000
	s_addc_u32 s23, s23, 0
	s_add_u32 s46, s46, 4
	s_addc_u32 s47, s47, 0
	s_waitcnt lgkmcnt(0)
	s_barrier
	s_sub_u32 s1, s1, 1
	s_cmp_lg_u32 s1, 0
	s_cbranch_scc1 .Lseq_loop
	s_waitcnt vmcnt(17)
	ds_read_b128 v[32:35], v213
	ds_read_b128 v[44:47], v213 offset:16384
	ds_read_b128 v[12:15], v214
	ds_read_b128 v[28:31], v214 offset:16384
	ds_read_b128 v[16:19], v215
	ds_read_b128 v[24:27], v215 offset:16384
	ds_read_b128 v[0:3], v216
	ds_read_b128 v[4:7], v216 offset:16384
	ds_read_b128 v[148:151], v246 offset:0
	ds_read_b128 v[192:195], v246 offset:4352
	ds_read_b128 v[196:199], v246 offset:64
	ds_read_b128 v[200:203], v246 offset:4416
	s_waitcnt lgkmcnt(4)
	s_waitcnt lgkmcnt(3)
	v_mfma_f32_16x16x32_bf16 v[92:95], v[32:35], v[148:151], 0
	v_mfma_f32_16x16x32_bf16 v[72:75], v[148:151], v[44:47], 0
	s_waitcnt lgkmcnt(2)
	v_mfma_f32_16x16x32_bf16 v[144:147], v[32:35], v[192:195], 0
	v_mfma_f32_16x16x32_bf16 v[76:79], v[192:195], v[44:47], 0
	ds_read_b128 v[148:151], v246 offset:128
	ds_read_b128 v[192:195], v246 offset:4480
	s_waitcnt lgkmcnt(3)
	v_mfma_f32_16x16x32_bf16 v[92:95], v[12:15], v[196:199], v[92:95]
	v_mfma_f32_16x16x32_bf16 v[72:75], v[196:199], v[28:31], v[72:75]
	s_waitcnt lgkmcnt(2)
	v_mfma_f32_16x16x32_bf16 v[144:147], v[12:15], v[200:203], v[144:147]
	v_mfma_f32_16x16x32_bf16 v[76:79], v[200:203], v[28:31], v[76:79]
	ds_read_b128 v[196:199], v246 offset:192
	ds_read_b128 v[200:203], v246 offset:4544
	s_waitcnt lgkmcnt(3)
	v_mfma_f32_16x16x32_bf16 v[92:95], v[16:19], v[148:151], v[92:95]
	v_mfma_f32_16x16x32_bf16 v[72:75], v[148:151], v[24:27], v[72:75]
	s_waitcnt lgkmcnt(2)
	v_mfma_f32_16x16x32_bf16 v[144:147], v[16:19], v[192:195], v[144:147]
	v_mfma_f32_16x16x32_bf16 v[76:79], v[192:195], v[24:27], v[76:79]
	s_waitcnt lgkmcnt(1)
	v_mfma_f32_16x16x32_bf16 v[92:95], v[0:3], v[196:199], v[92:95]
	v_mfma_f32_16x16x32_bf16 v[72:75], v[196:199], v[4:7], v[72:75]
	s_waitcnt lgkmcnt(0)
	v_mfma_f32_16x16x32_bf16 v[144:147], v[0:3], v[200:203], v[144:147]
	v_mfma_f32_16x16x32_bf16 v[76:79], v[200:203], v[4:7], v[76:79]
	s_waitcnt vmcnt(8)
	v_mov_b32_e32 v255, v88
	s_nop 7
	v_lshlrev_b32_e32 v242, 16, v186
	v_lshlrev_b32_e32 v243, 16, v188
	v_lshlrev_b32_e32 v244, 16, v185
	v_lshlrev_b32_e32 v245, 16, v89
	v_sub_f32_e32 v242, v242, v92
	v_sub_f32_e32 v243, v243, v93
	v_sub_f32_e32 v244, v244, v94
	v_sub_f32_e32 v245, v245, v95
	v_cvt_pk_bf16_f32 v242, v242, v243
	v_cvt_pk_bf16_f32 v243, v244, v245
	ds_write_b64 v247, v[242:243]
	v_lshlrev_b32_e32 v242, 16, v91
	v_lshlrev_b32_e32 v243, 16, v187
	v_lshlrev_b32_e32 v244, 16, v189
	v_lshlrev_b32_e32 v245, 16, v190
	v_sub_f32_e32 v242, v242, v144
	v_sub_f32_e32 v243, v243, v145
	v_sub_f32_e32 v244, v244, v146
	v_sub_f32_e32 v245, v245, v147
	v_cvt_pk_bf16_f32 v242, v242, v243
	v_cvt_pk_bf16_f32 v243, v244, v245
	ds_write_b64 v247, v[242:243] offset:2304
	s_waitcnt lgkmcnt(0)
	s_barrier
	s_waitcnt vmcnt(2)
	ds_read_b128 v[52:55], v221
	ds_read_b128 v[48:51], v222
	ds_read_b128 v[40:43], v217
	ds_read_b128 v[36:39], v220
	ds_read_b128 v[8:11], v217 offset:2048
	ds_read_b128 v[20:23], v220 offset:2048
	ds_read_b128 v[148:151], v248 offset:0
	ds_read_b128 v[192:195], v248 offset:2304
	ds_read_b128 v[196:199], v248 offset:64
	ds_read_b128 v[200:203], v248 offset:2368
	v_mul_f32_e32 v56, v56, v255
	v_mul_f32_e32 v57, v57, v255
	v_mul_f32_e32 v58, v58, v255
	v_mul_f32_e32 v59, v59, v255
	v_mul_f32_e32 v64, v64, v255
	v_mul_f32_e32 v65, v65, v255
	v_mul_f32_e32 v66, v66, v255
	v_mul_f32_e32 v67, v67, v255
	v_mul_f32_e32 v68, v68, v255
	v_mul_f32_e32 v69, v69, v255
	v_mul_f32_e32 v70, v70, v255
	v_mul_f32_e32 v71, v71, v255
	v_mul_f32_e32 v60, v60, v255
	v_mul_f32_e32 v61, v61, v255
	v_mul_f32_e32 v62, v62, v255
	v_mul_f32_e32 v63, v63, v255
	s_waitcnt lgkmcnt(4)
	s_waitcnt lgkmcnt(3)
	v_mfma_f32_16x16x32_bf16 v[72:75], v[148:151], v[52:55], v[72:75]
	s_waitcnt lgkmcnt(2)
	v_mfma_f32_16x16x32_bf16 v[76:79], v[192:195], v[52:55], v[76:79]
	s_waitcnt lgkmcnt(1)
	v_mfma_f32_16x16x32_bf16 v[72:75], v[196:199], v[48:51], v[72:75]
	s_waitcnt lgkmcnt(0)
	v_mfma_f32_16x16x32_bf16 v[76:79], v[200:203], v[48:51], v[76:79]
	v_mfma_f32_16x16x32_bf16 v[56:59], v[40:43], v[148:151], v[56:59]
	v_mfma_f32_16x16x32_bf16 v[64:67], v[40:43], v[192:195], v[64:67]
	v_mfma_f32_16x16x32_bf16 v[56:59], v[36:39], v[196:199], v[56:59]
	v_mfma_f32_16x16x32_bf16 v[64:67], v[36:39], v[200:203], v[64:67]
	v_mfma_f32_16x16x32_bf16 v[68:71], v[8:11], v[148:151], v[68:71]
	v_mfma_f32_16x16x32_bf16 v[60:63], v[8:11], v[192:195], v[60:63]
	v_mfma_f32_16x16x32_bf16 v[68:71], v[20:23], v[196:199], v[68:71]
	v_mfma_f32_16x16x32_bf16 v[60:63], v[20:23], v[200:203], v[60:63]
	s_nop 3
	global_store_dwordx4 v[86:87], v[72:75], off
	global_store_dwordx4 v[86:87], v[76:79], off offset:64
	s_nop 7
	v_cvt_pk_bf16_f32 v242, v56, v57
	v_cvt_pk_bf16_f32 v243, v58, v59
	ds_write_b64 v249, v[242:243]
	v_cvt_pk_bf16_f32 v242, v64, v65
	v_cvt_pk_bf16_f32 v243, v66, v67
	ds_write_b64 v249, v[242:243] offset:4352
	v_cvt_pk_bf16_f32 v242, v68, v69
	v_cvt_pk_bf16_f32 v243, v70, v71
	ds_write_b64 v249, v[242:243] offset:32
	v_cvt_pk_bf16_f32 v242, v60, v61
	v_cvt_pk_bf16_f32 v243, v62, v63
	ds_write_b64 v249, v[242:243] offset:4384
	v_lshl_add_u64 v[86:87], v[86:87], 0, s[50:51]
	s_add_u32 s20, s20, 0x12000
	s_addc_u32 s21, s21, 0
	s_add_u32 s22, s22, 0x12000
	s_addc_u32 s23, s23, 0
	s_add_u32 s46, s46, 4
	s_addc_u32 s47, s47, 0
	s_waitcnt lgkmcnt(0)
	s_barrier
	s_branch .LBB0_520
